# v18 plus GEMM2 epilogue (layers 1-3): second half's residual rows loaded with the first half's, counted vmcnt waits, compiler's vmcnt(0) store drains skipped on that path
# baseline (speedup 1.0000x reference)
.LBB0_393:
	s_and_b32 s0, s28, 1
	s_xor_b32 s29, s0, 1
	s_mul_i32 s29, s29, 0xc000
	s_add_i32 s34, s52, s29
	v_lshl_add_u64 v[94:95], v[92:93], 0, s[26:27]
	s_mul_i32 s0, s0, 0xc000
	s_add_i32 s29, s50, s29
	s_mov_b32 m0, s34
	v_lshl_add_u64 v[96:97], v[88:89], 0, s[26:27]
	s_add_i32 s0, s0, 0
	global_load_lds_dwordx4 v[94:95], off
	s_add_i32 m0, s29, 0x4000
	v_lshl_add_u64 v[98:99], v[86:87], 0, s[26:27]
	v_add_u32_e32 v80, s0, v153
	v_add_u32_e32 v139, s0, v154
	global_load_lds_dwordx4 v[96:97], off
	s_add_i32 m0, s29, 0x4400
	v_add_u32_e32 v146, v80, v151
	v_add_u32_e32 v110, v139, v151
	global_load_lds_dwordx4 v[98:99], off
	ds_read_b128 v[94:97], v146
	ds_read_b128 v[98:101], v110 offset:16384
	ds_read_b128 v[102:105], v110 offset:18432
	ds_read_b128 v[106:109], v110 offset:20480
	ds_read_b128 v[110:113], v110 offset:22528
	s_waitcnt lgkmcnt(0)
	v_mfma_f32_16x16x32_bf16 v[76:79], v[94:97], v[98:101], v[76:79]
	v_lshl_add_u64 v[140:141], v[90:91], 0, s[26:27]
	s_add_i32 s0, s29, 0x4800
	s_add_i32 m0, s34, 0x400
	v_mfma_f32_16x16x32_bf16 v[72:75], v[94:97], v[102:105], v[72:75]
	v_lshl_add_u64 v[142:143], v[82:83], 0, s[26:27]
	s_addk_i32 s29, 0x4c00
	v_lshl_add_u64 v[144:145], v[84:85], 0, s[26:27]
	v_mfma_f32_16x16x32_bf16 v[68:71], v[94:97], v[106:109], v[68:71]
	v_add_u32_e32 v80, v80, v152
	v_add_u32_e32 v139, v139, v152
	s_add_i32 s28, s28, 1
	v_mfma_f32_16x16x32_bf16 v[64:67], v[94:97], v[110:113], v[64:67]
	ds_read_b128 v[94:97], v146 offset:2048
	s_add_u32 s26, s26, 0x80
	s_addc_u32 s27, s27, 0
	s_waitcnt lgkmcnt(0)
	v_mfma_f32_16x16x32_bf16 v[60:63], v[94:97], v[98:101], v[60:63]
	s_cmpk_eq_i32 s26, 0x780
	v_mfma_f32_16x16x32_bf16 v[56:59], v[94:97], v[102:105], v[56:59]
	v_mfma_f32_16x16x32_bf16 v[52:55], v[94:97], v[106:109], v[52:55]
	v_mfma_f32_16x16x32_bf16 v[48:51], v[94:97], v[110:113], v[48:51]
	ds_read_b128 v[94:97], v146 offset:4096
	s_waitcnt lgkmcnt(0)
	v_mfma_f32_16x16x32_bf16 v[44:47], v[94:97], v[98:101], v[44:47]
	v_mfma_f32_16x16x32_bf16 v[40:43], v[94:97], v[102:105], v[40:43]
	v_mfma_f32_16x16x32_bf16 v[32:35], v[94:97], v[106:109], v[32:35]
	v_mfma_f32_16x16x32_bf16 v[24:27], v[94:97], v[110:113], v[24:27]
	ds_read_b128 v[94:97], v146 offset:6144
	global_load_lds_dwordx4 v[140:141], off
	s_mov_b32 m0, s0
	s_waitcnt lgkmcnt(0)
	v_mfma_f32_16x16x32_bf16 v[20:23], v[94:97], v[98:101], v[20:23]
	global_load_lds_dwordx4 v[142:143], off
	s_mov_b32 m0, s29
	v_mfma_f32_16x16x32_bf16 v[16:19], v[94:97], v[102:105], v[16:19]
	global_load_lds_dwordx4 v[144:145], off
	ds_read_b128 v[98:101], v80
	v_mfma_f32_16x16x32_bf16 v[36:39], v[94:97], v[106:109], v[36:39]
	ds_read_b128 v[102:105], v139 offset:18432
	ds_read_b128 v[106:109], v139 offset:20480
	v_mfma_f32_16x16x32_bf16 v[28:31], v[94:97], v[110:113], v[28:31]
	ds_read_b128 v[94:97], v139 offset:16384
	ds_read_b128 v[110:113], v139 offset:22528
	s_waitcnt lgkmcnt(0)
	v_mfma_f32_16x16x32_bf16 v[76:79], v[98:101], v[94:97], v[76:79]
	v_mfma_f32_16x16x32_bf16 v[72:75], v[98:101], v[102:105], v[72:75]
	v_mfma_f32_16x16x32_bf16 v[68:71], v[98:101], v[106:109], v[68:71]
	v_mfma_f32_16x16x32_bf16 v[64:67], v[98:101], v[110:113], v[64:67]
	ds_read_b128 v[98:101], v80 offset:2048
	s_waitcnt lgkmcnt(0)
	v_mfma_f32_16x16x32_bf16 v[60:63], v[98:101], v[94:97], v[60:63]
	v_mfma_f32_16x16x32_bf16 v[56:59], v[98:101], v[102:105], v[56:59]
	v_mfma_f32_16x16x32_bf16 v[52:55], v[98:101], v[106:109], v[52:55]
	v_mfma_f32_16x16x32_bf16 v[48:51], v[98:101], v[110:113], v[48:51]
	ds_read_b128 v[98:101], v80 offset:4096
	s_waitcnt lgkmcnt(0)
	v_mfma_f32_16x16x32_bf16 v[44:47], v[98:101], v[94:97], v[44:47]
	v_mfma_f32_16x16x32_bf16 v[40:43], v[98:101], v[102:105], v[40:43]
	v_mfma_f32_16x16x32_bf16 v[32:35], v[98:101], v[106:109], v[32:35]
	v_mfma_f32_16x16x32_bf16 v[24:27], v[98:101], v[110:113], v[24:27]
	ds_read_b128 v[98:101], v80 offset:6144
	s_waitcnt vmcnt(0)
	s_waitcnt vmcnt(0) lgkmcnt(0)
	v_mfma_f32_16x16x32_bf16 v[20:23], v[98:101], v[94:97], v[20:23]
	s_barrier
	v_mfma_f32_16x16x32_bf16 v[16:19], v[98:101], v[102:105], v[16:19]
	v_mfma_f32_16x16x32_bf16 v[36:39], v[98:101], v[106:109], v[36:39]
	v_mfma_f32_16x16x32_bf16 v[28:31], v[98:101], v[110:113], v[28:31]
	s_cbranch_scc0 .LBB0_393
	v_add_u32_e32 v80, v155, v151
	ds_read_b128 v[82:85], v80 offset:49152
	v_add_u32_e32 v110, v156, v151
	ds_read_b128 v[86:89], v110 offset:16384
	ds_read_b128 v[90:93], v80 offset:51200
	ds_read_b128 v[94:97], v110 offset:18432
	ds_read_b128 v[98:101], v80 offset:53248
	ds_read_b128 v[102:105], v110 offset:20480
	ds_read_b128 v[106:109], v80 offset:55296
	ds_read_b128 v[110:113], v110 offset:22528
	s_waitcnt lgkmcnt(5)
	v_mfma_f32_16x16x32_bf16 v[60:63], v[90:93], v[86:89], v[60:63]
	s_or_b32 s26, s19, s54
	s_lshl_b32 s0, s73, 8
	s_ashr_i32 s27, s26, 31
	s_waitcnt lgkmcnt(3)
	v_mfma_f32_16x16x32_bf16 v[44:47], v[98:101], v[86:89], v[44:47]
	v_mov_b32_e32 v139, v188
	s_add_i32 s28, s0, s51
	s_lshl_b64 s[34:35], s[26:27], 1
	v_mfma_f32_16x16x32_bf16 v[76:79], v[82:85], v[86:89], v[76:79]
	s_add_u32 s40, s55, s34
	s_addc_u32 s41, s56, s35
	s_ashr_i32 s29, s28, 31
	s_waitcnt lgkmcnt(1)
	v_mfma_f32_16x16x32_bf16 v[86:89], v[106:109], v[86:89], v[20:23]
	s_and_b64 vcc, exec, s[8:9]
	s_nop 1
	v_add_u32_e32 v20, v155, v152
	v_mfma_f32_16x16x32_bf16 v[144:147], v[106:109], v[94:97], v[16:19]
	v_add_u32_e32 v21, v156, v152
	s_nop 1
	ds_read_b128 v[16:19], v20 offset:49152
	v_mfma_f32_16x16x32_bf16 v[72:75], v[82:85], v[94:97], v[72:75]
	v_mfma_f32_16x16x32_bf16 v[140:143], v[82:85], v[102:105], v[68:71]
	s_waitcnt lgkmcnt(1)
	v_mfma_f32_16x16x32_bf16 v[82:85], v[82:85], v[110:113], v[64:67]
	v_mfma_f32_16x16x32_bf16 v[56:59], v[90:93], v[94:97], v[56:59]
	v_mfma_f32_16x16x32_bf16 v[52:55], v[90:93], v[102:105], v[52:55]
	v_mfma_f32_16x16x32_bf16 v[48:51], v[90:93], v[110:113], v[48:51]
	v_mfma_f32_16x16x32_bf16 v[40:43], v[98:101], v[94:97], v[40:43]
	v_mfma_f32_16x16x32_bf16 v[32:35], v[98:101], v[102:105], v[32:35]
	v_mfma_f32_16x16x32_bf16 v[98:101], v[98:101], v[110:113], v[24:27]
	v_mfma_f32_16x16x32_bf16 v[36:39], v[106:109], v[102:105], v[36:39]
	v_mfma_f32_16x16x32_bf16 v[102:105], v[106:109], v[110:113], v[28:31]
	ds_read_b128 v[94:97], v21 offset:16384
	ds_read_b128 v[24:27], v20 offset:51200
	ds_read_b128 v[106:109], v21 offset:18432
	ds_read_b128 v[110:113], v20 offset:53248
	ds_read_b128 v[158:161], v21 offset:20480
	ds_read_b128 v[162:165], v20 offset:55296
	ds_read_b128 v[166:169], v21 offset:22528
	s_waitcnt vmcnt(0)
	s_waitcnt lgkmcnt(0)
	v_mfma_f32_16x16x32_bf16 v[68:71], v[16:19], v[94:97], v[76:79]
	s_barrier
	v_mfma_f32_16x16x32_bf16 v[64:67], v[16:19], v[106:109], v[72:75]
	v_mfma_f32_16x16x32_bf16 v[20:23], v[16:19], v[158:161], v[140:143]
	v_mfma_f32_16x16x32_bf16 v[16:19], v[16:19], v[166:169], v[82:85]
	s_nop 1
	v_ashrrev_i32_e32 v140, 3, v139
	v_ashrrev_i32_e32 v141, 31, v140
	v_mfma_f32_16x16x32_bf16 v[76:79], v[24:27], v[94:97], v[60:63]
	v_mfma_f32_16x16x32_bf16 v[72:75], v[24:27], v[106:109], v[56:59]
	v_mfma_f32_16x16x32_bf16 v[28:31], v[24:27], v[158:161], v[52:55]
	v_mfma_f32_16x16x32_bf16 v[24:27], v[24:27], v[166:169], v[48:51]
	v_mfma_f32_16x16x32_bf16 v[90:93], v[110:113], v[94:97], v[44:47]
	v_mfma_f32_16x16x32_bf16 v[82:85], v[110:113], v[106:109], v[40:43]
	v_mfma_f32_16x16x32_bf16 v[40:43], v[110:113], v[158:161], v[32:35]
	v_mfma_f32_16x16x32_bf16 v[32:35], v[110:113], v[166:169], v[98:101]
	v_mfma_f32_16x16x32_bf16 v[94:97], v[162:165], v[94:97], v[86:89]
	v_mfma_f32_16x16x32_bf16 v[86:89], v[162:165], v[106:109], v[144:147]
	v_mfma_f32_16x16x32_bf16 v[44:47], v[162:165], v[158:161], v[36:39]
	v_and_b32_e32 v159, 7, v139
	v_lshlrev_b32_e32 v80, 4, v159
	v_lshl_add_u64 v[142:143], s[40:41], 0, v[80:81]
	v_mfma_f32_16x16x32_bf16 v[36:39], v[162:165], v[166:169], v[102:105]
	s_lshl_b64 s[40:41], s[28:29], 11
	v_lshl_add_u64 v[144:145], v[142:143], 0, s[40:41]
	s_mov_b64 s[40:41], -1
	s_mov_b32 s100, 0
	s_cbranch_vccz .LBB0_396
	v_lshlrev_b64 v[146:147], 11, v[140:141]
	v_lshl_add_u64 v[60:61], v[144:145], 0, v[146:147]
	s_movk_i32 s0, 0x4000
	v_add_co_u32_e32 v52, vcc, s0, v60
	s_mov_b32 s0, 0x8000
	s_nop 0
	v_addc_co_u32_e32 v53, vcc, 0, v61, vcc
	v_add_co_u32_e32 v56, vcc, s0, v60
	s_mov_b32 s0, 0xc000
	s_nop 0
	v_addc_co_u32_e32 v57, vcc, 0, v61, vcc
	global_load_dwordx4 v[48:51], v[60:61], off
	v_add_co_u32_e32 v60, vcc, s0, v60
	global_load_dwordx4 v[52:55], v[52:53], off
	s_nop 0
	v_addc_co_u32_e32 v61, vcc, 0, v61, vcc
	global_load_dwordx4 v[56:59], v[56:57], off
	s_mov_b64 s[40:41], 0
	s_mov_b32 s100, 1
	global_load_dwordx4 v[170:173], v[60:61], off
	v_add_co_u32_e32 v174, vcc, 0x4000, v60
	s_nop 1
	v_addc_co_u32_e32 v175, vcc, 0, v61, vcc
	global_load_dwordx4 v[182:185], v[174:175], off
	v_add_co_u32_e32 v174, vcc, 0x4000, v174
	s_nop 1
	v_addc_co_u32_e32 v175, vcc, 0, v175, vcc
	global_load_dwordx4 v[190:193], v[174:175], off
	v_add_co_u32_e32 v174, vcc, 0x4000, v174
	s_nop 1
	v_addc_co_u32_e32 v175, vcc, 0, v175, vcc
	global_load_dwordx4 v[194:197], v[174:175], off
	v_add_co_u32_e32 v174, vcc, 0x4000, v174
	s_nop 1
	v_addc_co_u32_e32 v175, vcc, 0, v175, vcc
	global_load_dwordx4 v[198:201], v[174:175], off

.LBB0_402:
	v_and_b32_e32 v80, 15, v139
	v_mov_b32_e32 v158, s53
	v_mad_u32_u24 v80, v80, s77, v158
	v_and_b32_e32 v139, -16, v139
	v_add_u32_e32 v158, v80, v139
	ds_write_b128 v158, v[68:71]
	ds_write_b128 v158, v[76:79] offset:64
	ds_write_b128 v158, v[90:93] offset:128
	ds_write_b128 v158, v[94:97] offset:192
	v_lshl_add_u32 v160, v157, 2, s53
	s_nop 1
	ds_write_b128 v158, v[64:67] offset:4352
	ds_write_b128 v158, v[72:75] offset:4416
	ds_write_b128 v158, v[82:85] offset:4480
	ds_write_b128 v158, v[86:89] offset:4544
	v_mul_lo_u32 v64, v140, s77
	v_add_u32_e32 v139, v160, v64
	s_nop 1
	ds_read_b128 v[64:67], v139
	ds_read_b128 v[74:77], v139 offset:16
	s_cmp_eq_u32 s100, 0
	s_cbranch_scc1 .Lg2_res0
	s_waitcnt vmcnt(4)
	v_lshlrev_b32_e32 v110, 16, v48
	v_and_b32_e32 v111, 0xffff0000, v48
	v_lshlrev_b32_e32 v112, 16, v49
	v_and_b32_e32 v113, 0xffff0000, v49
	v_lshlrev_b32_e32 v106, 16, v50
	v_and_b32_e32 v107, 0xffff0000, v50
	v_lshlrev_b32_e32 v108, 16, v51
	v_and_b32_e32 v109, 0xffff0000, v51
	v_lshlrev_b32_e32 v102, 16, v52
	v_and_b32_e32 v103, 0xffff0000, v52
	v_lshlrev_b32_e32 v104, 16, v53
	v_and_b32_e32 v105, 0xffff0000, v53
	v_lshlrev_b32_e32 v98, 16, v54
	v_and_b32_e32 v99, 0xffff0000, v54
	v_lshlrev_b32_e32 v100, 16, v55
	v_and_b32_e32 v101, 0xffff0000, v55
	v_lshlrev_b32_e32 v60, 16, v56
	v_and_b32_e32 v61, 0xffff0000, v56
	v_lshlrev_b32_e32 v62, 16, v57
	v_and_b32_e32 v63, 0xffff0000, v57
	v_lshlrev_b32_e32 v56, 16, v58
	v_and_b32_e32 v57, 0xffff0000, v58
	v_lshlrev_b32_e32 v58, 16, v59
	v_and_b32_e32 v59, 0xffff0000, v59
	v_lshlrev_b32_e32 v52, 16, v170
	v_and_b32_e32 v53, 0xffff0000, v170
	v_lshlrev_b32_e32 v54, 16, v171
	v_and_b32_e32 v55, 0xffff0000, v171
	v_lshlrev_b32_e32 v48, 16, v172
	v_and_b32_e32 v49, 0xffff0000, v172
	v_lshlrev_b32_e32 v50, 16, v173
	v_and_b32_e32 v51, 0xffff0000, v173

.LBB0_410:
	s_waitcnt lgkmcnt(0)
	ds_read_b128 v[64:67], v139 offset:2176
	ds_read_b128 v[76:79], v139 offset:2192
	v_add_u32_e32 v84, 8, v140
	v_ashrrev_i32_e32 v85, 31, v84
	v_lshlrev_b64 v[68:69], 11, v[84:85]
	s_waitcnt lgkmcnt(0)
	s_cmp_eq_u32 s100, 1
	s_cbranch_scc1 .Lg2_nd0
	s_waitcnt vmcnt(0)
.Lg2_nd0:
	v_pk_fma_f32 v[70:71], v[12:13], v[64:65], v[102:103]
	v_pk_fma_f32 v[74:75], v[14:15], v[66:67], v[104:105]
	v_pk_fma_f32 v[72:73], v[8:9], v[76:77], v[98:99]
	v_pk_fma_f32 v[76:77], v[10:11], v[78:79], v[100:101]
	v_cndmask_b32_e64 v80, 0, 1, s[12:13]
	v_cvt_pk_bf16_f32 v64, v70, v71
	v_cvt_pk_bf16_f32 v65, v74, v75
	v_cvt_pk_bf16_f32 v66, v72, v73
	v_cvt_pk_bf16_f32 v67, v76, v77
	v_lshl_add_u64 v[78:79], v[144:145], 0, v[68:69]
	v_cmp_ne_u32_e64 s[44:45], 1, v80
	s_andn2_b64 vcc, exec, s[12:13]
	s_mov_b64 s[34:35], -1
	s_cbranch_vccnz .LBB0_412
	s_mov_b64 s[34:35], 0
	global_store_dwordx4 v[78:79], v[64:67], off

.LBB0_434:
	s_or_b32 s34, s28, 32
	s_ashr_i32 s35, s34, 31
	s_lshl_b64 s[46:47], s[34:35], 11
	v_lshl_add_u64 v[48:49], v[142:143], 0, s[46:47]
	s_mov_b64 s[46:47], -1
	s_andn2_b64 vcc, exec, s[8:9]
	v_lshl_add_u64 v[96:97], v[48:49], 0, v[146:147]
	v_lshl_add_u64 v[94:95], v[48:49], 0, v[68:69]
	v_lshl_add_u64 v[92:93], v[48:49], 0, v[60:61]
	v_lshl_add_u64 v[90:91], v[48:49], 0, v[52:53]
	s_mov_b32 s101, 0
	s_cbranch_vccnz .LBB0_436
	s_mov_b64 s[46:47], 0
	s_mov_b32 s101, 1

.LBB0_442:
	ds_write_b128 v158, v[20:23]
	ds_write_b128 v158, v[28:31] offset:64
	ds_write_b128 v158, v[40:43] offset:128
	ds_write_b128 v158, v[44:47] offset:192
	s_nop 1
	ds_write_b128 v158, v[16:19] offset:4352
	ds_write_b128 v158, v[24:27] offset:4416
	ds_write_b128 v158, v[32:35] offset:4480
	ds_write_b128 v158, v[36:39] offset:4544
	s_nop 1
	ds_read_b128 v[16:19], v139
	ds_read_b128 v[26:29], v139 offset:16
	s_cmp_eq_u32 s101, 0
	s_cbranch_scc1 .Lg2_res1
	s_waitcnt vmcnt(8)
	v_lshlrev_b32_e32 v76, 16, v182
	v_and_b32_e32 v77, 0xffff0000, v182
	v_lshlrev_b32_e32 v78, 16, v183
	v_and_b32_e32 v79, 0xffff0000, v183
	v_lshlrev_b32_e32 v72, 16, v184
	v_and_b32_e32 v73, 0xffff0000, v184
	v_lshlrev_b32_e32 v74, 16, v185
	v_and_b32_e32 v75, 0xffff0000, v185
	v_lshlrev_b32_e32 v68, 16, v190
	v_and_b32_e32 v69, 0xffff0000, v190
	v_lshlrev_b32_e32 v70, 16, v191
	v_and_b32_e32 v71, 0xffff0000, v191
	v_lshlrev_b32_e32 v64, 16, v192
	v_and_b32_e32 v65, 0xffff0000, v192
	v_lshlrev_b32_e32 v66, 16, v193
	v_and_b32_e32 v67, 0xffff0000, v193
	v_lshlrev_b32_e32 v60, 16, v194
	v_and_b32_e32 v61, 0xffff0000, v194
	v_lshlrev_b32_e32 v62, 16, v195
	v_and_b32_e32 v63, 0xffff0000, v195
	v_lshlrev_b32_e32 v56, 16, v196
	v_and_b32_e32 v57, 0xffff0000, v196
	v_lshlrev_b32_e32 v58, 16, v197
	v_and_b32_e32 v59, 0xffff0000, v197
	v_lshlrev_b32_e32 v52, 16, v198
	v_and_b32_e32 v53, 0xffff0000, v198
	v_lshlrev_b32_e32 v54, 16, v199
	v_and_b32_e32 v55, 0xffff0000, v199
	v_lshlrev_b32_e32 v48, 16, v200
	v_and_b32_e32 v49, 0xffff0000, v200
	v_lshlrev_b32_e32 v50, 16, v201
	v_and_b32_e32 v51, 0xffff0000, v201
.Lg2_res1:
	s_and_b64 vcc, exec, s[44:45]
	s_mov_b64 s[16:17], -1
	s_waitcnt lgkmcnt(0)
	s_cmp_eq_u32 s101, 1
	s_cbranch_scc1 .Lg2_nd1
	s_waitcnt vmcnt(0)
.Lg2_nd1:
	v_pk_fma_f32 v[20:21], v[12:13], v[16:17], v[76:77]
	v_pk_fma_f32 v[24:25], v[14:15], v[18:19], v[78:79]
	v_pk_fma_f32 v[22:23], v[8:9], v[26:27], v[72:73]
	v_pk_fma_f32 v[26:27], v[10:11], v[28:29], v[74:75]
	v_cvt_pk_bf16_f32 v16, v20, v21
	v_cvt_pk_bf16_f32 v17, v24, v25
	v_cvt_pk_bf16_f32 v18, v22, v23
	v_cvt_pk_bf16_f32 v19, v26, v27
	s_cbranch_vccnz .LBB0_444
	s_mov_b64 s[16:17], 0
	global_store_dwordx4 v[96:97], v[16:19], off
